# prep: idle wave 1 in section D touches the next item's UC lines (L2 prefetch) so section B's loads hit L2
# baseline (speedup 1.0000x reference)
.Lpd_inv:
	s_add_i32 s36, s23, s74
	s_ashr_i32 s37, s36, 10
	s_lshl_b32 s37, s37, 13
	s_and_b32 s38, s36, 0x7f
	s_lshl_b32 s38, s38, 6
	s_add_u32 s37, s37, s38
	v_add_u32_e32 v4, s37, v134
	v_lshlrev_b32_e32 v4, 6, v4
	s_bfe_u32 s38, s36, 0x30007
	s_lshl_b32 s38, s38, 2
	v_add_u32_e32 v4, s38, v4
	v_mov_b32_e32 v5, s38
	v_readlane_b32 s40, v251, 53
	v_readlane_b32 s41, v251, 54
	v_readlane_b32 s44, v251, 55
	v_readlane_b32 s45, v251, 56
	global_load_dword v242, v4, s[14:15]
	global_load_dword v243, v4, s[14:15] offset:32
	s_nop 2
	global_load_dword v244, v5, s[40:41]
	global_load_dword v245, v5, s[44:45]
	v_lshrrev_b32_e32 v2, 4, v135
	v_mul_u32_u24_e32 v2, 0x1140, v2
	ds_read_b128 v[136:139], v2 offset:52224
	ds_read_b128 v[140:143], v2 offset:52240
	ds_read_b128 v[144:147], v2 offset:52256
	ds_read_b128 v[148:151], v2 offset:52272
	ds_read_b128 v[168:171], v2 offset:52496
	ds_read_b128 v[172:175], v2 offset:52512
	ds_read_b128 v[176:179], v2 offset:52528
	ds_read_b128 v[184:187], v2 offset:52544
	ds_read_b128 v[188:191], v2 offset:52768
	ds_read_b128 v[192:195], v2 offset:52784
	ds_read_b128 v[196:199], v2 offset:52800
	ds_read_b128 v[200:203], v2 offset:52816
	ds_read_b128 v[234:237], v2 offset:53056
	ds_read_b128 v[238:241], v2 offset:53072
	ds_read_b128 v[30:33], v2 offset:53088
	ds_read_b128 v[34:37], v2 offset:53328
	ds_read_b128 v[42:45], v2 offset:53344
	ds_read_b128 v[160:163], v2 offset:53360
	v_cmp_eq_u32_e64 s[0:1], 0, v1
	v_cmp_eq_u32_e64 s[2:3], 1, v1
	v_cmp_eq_u32_e64 s[4:5], 2, v1
	v_cmp_eq_u32_e64 s[6:7], 3, v1
	v_cmp_eq_u32_e64 s[28:29], 4, v1
	v_cmp_eq_u32_e64 s[30:31], 5, v1
	v_cmp_eq_u32_e64 s[32:33], 6, v1
	v_cmp_eq_u32_e64 s[34:35], 7, v1
	v_cndmask_b32_e64 v8, 0, 1.0, s[0:1]
	v_cndmask_b32_e64 v9, 0, 1.0, s[2:3]
	v_cndmask_b32_e64 v10, 0, 1.0, s[4:5]
	v_cndmask_b32_e64 v11, 0, 1.0, s[6:7]
	v_cndmask_b32_e64 v12, 0, 1.0, s[28:29]
	v_cndmask_b32_e64 v13, 0, 1.0, s[30:31]
	v_cndmask_b32_e64 v14, 0, 1.0, s[32:33]
	v_cndmask_b32_e64 v15, 0, 1.0, s[34:35]
	v_cmp_eq_u32_e64 s[0:1], 8, v1
	v_cmp_eq_u32_e64 s[2:3], 9, v1
	v_cmp_eq_u32_e64 s[4:5], 10, v1
	v_cmp_eq_u32_e64 s[6:7], 11, v1
	v_cmp_eq_u32_e64 s[28:29], 12, v1
	v_cmp_eq_u32_e64 s[30:31], 13, v1
	v_cmp_eq_u32_e64 s[32:33], 14, v1
	v_cmp_eq_u32_e64 s[34:35], 15, v1
	v_cndmask_b32_e64 v16, 0, 1.0, s[0:1]
	v_cndmask_b32_e64 v17, 0, 1.0, s[2:3]
	v_cndmask_b32_e64 v18, 0, 1.0, s[4:5]
	v_cndmask_b32_e64 v19, 0, 1.0, s[6:7]
	v_cndmask_b32_e64 v20, 0, 1.0, s[28:29]
	v_cndmask_b32_e64 v21, 0, 1.0, s[30:31]
	v_cndmask_b32_e64 v22, 0, 1.0, s[32:33]
	v_cndmask_b32_e64 v23, 0, 1.0, s[34:35]
	v_readlane_b32 s2, v251, 5
	v_lshlrev_b32_e32 v3, 5, v135
	v_and_b32_e32 v3, 0xfffffe00, v3
	v_lshl_add_u32 v3, v1, 1, v3
	v_add_u32_e32 v3, s2, v3
	s_waitcnt lgkmcnt(14)
	v_fma_f32 v9, -v8, v137, v9
	v_fma_f32 v10, -v8, v138, v10
	v_fma_f32 v11, -v8, v139, v11
	v_fma_f32 v12, -v8, v140, v12
	v_fma_f32 v13, -v8, v141, v13
	v_fma_f32 v14, -v8, v142, v14
	v_fma_f32 v15, -v8, v143, v15
	v_fma_f32 v16, -v8, v144, v16
	v_fma_f32 v17, -v8, v145, v17
	v_fma_f32 v18, -v8, v146, v18
	v_fma_f32 v19, -v8, v147, v19
	v_fma_f32 v20, -v8, v148, v20
	v_fma_f32 v21, -v8, v149, v21
	v_fma_f32 v22, -v8, v150, v22
	v_fma_f32 v23, -v8, v151, v23
	ds_read_b128 v[136:139], v2 offset:53600
	ds_read_b128 v[140:143], v2 offset:53616
	ds_read_b128 v[144:147], v2 offset:53632
	ds_read_b128 v[148:151], v2 offset:53872
	s_waitcnt lgkmcnt(14)
	v_fma_f32 v10, -v9, v170, v10
	v_fma_f32 v11, -v9, v171, v11
	v_fma_f32 v12, -v9, v172, v12
	v_fma_f32 v13, -v9, v173, v13
	v_fma_f32 v14, -v9, v174, v14
	v_fma_f32 v15, -v9, v175, v15
	v_fma_f32 v16, -v9, v176, v16
	v_fma_f32 v17, -v9, v177, v17
	v_fma_f32 v18, -v9, v178, v18
	v_fma_f32 v19, -v9, v179, v19
	v_fma_f32 v20, -v9, v184, v20
	v_fma_f32 v21, -v9, v185, v21
	v_fma_f32 v22, -v9, v186, v22
	v_fma_f32 v23, -v9, v187, v23
	ds_read_b128 v[168:171], v2 offset:53888
	ds_read_b128 v[172:175], v2 offset:53904
	ds_read_b128 v[176:179], v2 offset:54160
	ds_read_b128 v[184:187], v2 offset:54176
	s_waitcnt lgkmcnt(14)
	v_fma_f32 v11, -v10, v191, v11
	v_fma_f32 v12, -v10, v192, v12
	v_fma_f32 v13, -v10, v193, v13
	v_fma_f32 v14, -v10, v194, v14
	v_fma_f32 v15, -v10, v195, v15
	v_fma_f32 v16, -v10, v196, v16
	v_fma_f32 v17, -v10, v197, v17
	v_fma_f32 v18, -v10, v198, v18
	v_fma_f32 v19, -v10, v199, v19
	v_fma_f32 v20, -v10, v200, v20
	v_fma_f32 v21, -v10, v201, v21
	v_fma_f32 v22, -v10, v202, v22
	v_fma_f32 v23, -v10, v203, v23
	ds_read_b128 v[188:191], v2 offset:54432
	ds_read_b128 v[192:195], v2 offset:54448
	ds_read_b128 v[196:199], v2 offset:54704
	ds_read_b128 v[200:203], v2 offset:54720
	s_waitcnt lgkmcnt(14)
	v_fma_f32 v12, -v11, v234, v12
	v_fma_f32 v13, -v11, v235, v13
	v_fma_f32 v14, -v11, v236, v14
	v_fma_f32 v15, -v11, v237, v15
	v_fma_f32 v16, -v11, v238, v16
	v_fma_f32 v17, -v11, v239, v17
	v_fma_f32 v18, -v11, v240, v18
	v_fma_f32 v19, -v11, v241, v19
	v_fma_f32 v20, -v11, v30, v20
	v_fma_f32 v21, -v11, v31, v21
	v_fma_f32 v22, -v11, v32, v22
	v_fma_f32 v23, -v11, v33, v23
	ds_read_b128 v[234:237], v2 offset:54976
	ds_read_b128 v[238:241], v2 offset:54992
	ds_read_b128 v[30:33], v2 offset:55264
	s_waitcnt lgkmcnt(14)
	v_fma_f32 v13, -v12, v35, v13
	v_fma_f32 v14, -v12, v36, v14
	v_fma_f32 v15, -v12, v37, v15
	v_fma_f32 v16, -v12, v42, v16
	v_fma_f32 v17, -v12, v43, v17
	v_fma_f32 v18, -v12, v44, v18
	v_fma_f32 v19, -v12, v45, v19
	v_fma_f32 v20, -v12, v160, v20
	v_fma_f32 v21, -v12, v161, v21
	v_fma_f32 v22, -v12, v162, v22
	v_fma_f32 v23, -v12, v163, v23
	ds_read_b128 v[34:37], v2 offset:55536
	ds_read_b128 v[42:45], v2 offset:55808
	ds_read_b128 v[160:163], v2 offset:56080
	s_waitcnt lgkmcnt(14)
	v_fma_f32 v14, -v13, v138, v14
	v_fma_f32 v15, -v13, v139, v15
	v_fma_f32 v16, -v13, v140, v16
	v_fma_f32 v17, -v13, v141, v17
	v_fma_f32 v18, -v13, v142, v18
	v_fma_f32 v19, -v13, v143, v19
	v_fma_f32 v20, -v13, v144, v20
	v_fma_f32 v21, -v13, v145, v21
	v_fma_f32 v22, -v13, v146, v22
	v_fma_f32 v23, -v13, v147, v23
	s_waitcnt lgkmcnt(12)
	v_fma_f32 v15, -v14, v151, v15
	v_fma_f32 v16, -v14, v168, v16
	v_fma_f32 v17, -v14, v169, v17
	v_fma_f32 v18, -v14, v170, v18
	v_fma_f32 v19, -v14, v171, v19
	v_fma_f32 v20, -v14, v172, v20
	v_fma_f32 v21, -v14, v173, v21
	v_fma_f32 v22, -v14, v174, v22
	v_fma_f32 v23, -v14, v175, v23
	s_waitcnt lgkmcnt(10)
	v_fma_f32 v16, -v15, v176, v16
	v_fma_f32 v17, -v15, v177, v17
	v_fma_f32 v18, -v15, v178, v18
	v_fma_f32 v19, -v15, v179, v19
	v_fma_f32 v20, -v15, v184, v20
	v_fma_f32 v21, -v15, v185, v21
	v_fma_f32 v22, -v15, v186, v22
	v_fma_f32 v23, -v15, v187, v23
	s_waitcnt lgkmcnt(8)
	v_fma_f32 v17, -v16, v189, v17
	v_fma_f32 v18, -v16, v190, v18
	v_fma_f32 v19, -v16, v191, v19
	v_fma_f32 v20, -v16, v192, v20
	v_fma_f32 v21, -v16, v193, v21
	v_fma_f32 v22, -v16, v194, v22
	v_fma_f32 v23, -v16, v195, v23
	s_waitcnt lgkmcnt(6)
	v_fma_f32 v18, -v17, v198, v18
	v_fma_f32 v19, -v17, v199, v19
	v_fma_f32 v20, -v17, v200, v20
	v_fma_f32 v21, -v17, v201, v21
	v_fma_f32 v22, -v17, v202, v22
	v_fma_f32 v23, -v17, v203, v23
	s_waitcnt lgkmcnt(4)
	v_fma_f32 v19, -v18, v237, v19
	v_fma_f32 v20, -v18, v238, v20
	v_fma_f32 v21, -v18, v239, v21
	v_fma_f32 v22, -v18, v240, v22
	v_fma_f32 v23, -v18, v241, v23
	s_waitcnt lgkmcnt(3)
	v_fma_f32 v20, -v19, v30, v20
	v_fma_f32 v21, -v19, v31, v21
	v_fma_f32 v22, -v19, v32, v22
	v_fma_f32 v23, -v19, v33, v23
	s_waitcnt lgkmcnt(2)
	v_fma_f32 v21, -v20, v35, v21
	v_fma_f32 v22, -v20, v36, v22
	v_fma_f32 v23, -v20, v37, v23
	s_waitcnt lgkmcnt(1)
	v_fma_f32 v22, -v21, v44, v22
	v_fma_f32 v23, -v21, v45, v23
	s_waitcnt lgkmcnt(0)
	v_fma_f32 v23, -v22, v163, v23
	v_cvt_pk_bf16_f32 v8, v8, v8
	v_cvt_pk_bf16_f32 v9, v9, v9
	v_cvt_pk_bf16_f32 v10, v10, v10
	v_cvt_pk_bf16_f32 v11, v11, v11
	v_cvt_pk_bf16_f32 v12, v12, v12
	v_cvt_pk_bf16_f32 v13, v13, v13
	v_cvt_pk_bf16_f32 v14, v14, v14
	v_cvt_pk_bf16_f32 v15, v15, v15
	v_cvt_pk_bf16_f32 v16, v16, v16
	v_cvt_pk_bf16_f32 v17, v17, v17
	v_cvt_pk_bf16_f32 v18, v18, v18
	v_cvt_pk_bf16_f32 v19, v19, v19
	v_cvt_pk_bf16_f32 v20, v20, v20
	v_cvt_pk_bf16_f32 v21, v21, v21
	v_cvt_pk_bf16_f32 v22, v22, v22
	v_cvt_pk_bf16_f32 v23, v23, v23
	ds_write_b16 v3, v8
	ds_write_b16 v3, v9 offset:32
	ds_write_b16 v3, v10 offset:64
	ds_write_b16 v3, v11 offset:96
	ds_write_b16 v3, v12 offset:128
	ds_write_b16 v3, v13 offset:160
	ds_write_b16 v3, v14 offset:192
	ds_write_b16 v3, v15 offset:224
	ds_write_b16 v3, v16 offset:256
	ds_write_b16 v3, v17 offset:288
	ds_write_b16 v3, v18 offset:320
	ds_write_b16 v3, v19 offset:352
	ds_write_b16 v3, v20 offset:384
	ds_write_b16 v3, v21 offset:416
	ds_write_b16 v3, v22 offset:448
	ds_write_b16 v3, v23 offset:480
	s_branch .Lpd_done
.Lpd_l2pf:
	s_cmp_eq_u32 s26, 1
	s_cbranch_scc0 .Lpd_done
	s_add_i32 s36, s23, s74
	s_ashr_i32 s37, s36, 10
	s_lshl_b32 s37, s37, 13
	s_and_b32 s38, s36, 0x7f
	s_lshl_b32 s38, s38, 6
	s_sub_u32 s38, s38, 3
	s_bfe_u32 s39, s36, 0x30007
	s_lshr_b32 s40, s39, 1
	s_lshl_b32 s39, s39, 8
	s_lshl_b32 s40, s40, 8
	v_mov_b32_e32 v10, s39
	v_mov_b32_e32 v11, s40
	v_add_u32_e32 v2, 0, v134
	v_mul_u32_u24_e32 v3, 0x2aab, v2
	v_lshrrev_b32_e32 v3, 16, v3
	v_mul_u32_u24_e32 v4, 6, v3
	v_sub_u32_e32 v4, v2, v4
	v_add_u32_e32 v5, s38, v3
	v_max_i32_e32 v5, 0, v5
	v_add_u32_e32 v5, s37, v5
	v_lshlrev_b32_e32 v5, 12, v5
	v_lshrrev_b32_e32 v6, 1, v4
	v_cmp_eq_u32_e32 vcc, 2, v6
	v_lshl_add_u32 v5, v6, 10, v5
	v_and_b32_e32 v4, 1, v4
	v_cndmask_b32_e32 v7, v11, v10, vcc
	v_lshl_add_u32 v5, v4, 7, v5
	v_add_u32_e32 v5, v7, v5
	global_load_dword v233, v5, s[12:13]
	v_add_u32_e32 v2, 64, v134
	v_mul_u32_u24_e32 v3, 0x2aab, v2
	v_lshrrev_b32_e32 v3, 16, v3
	v_mul_u32_u24_e32 v4, 6, v3
	v_sub_u32_e32 v4, v2, v4
	v_add_u32_e32 v5, s38, v3
	v_max_i32_e32 v5, 0, v5
	v_add_u32_e32 v5, s37, v5
	v_lshlrev_b32_e32 v5, 12, v5
	v_lshrrev_b32_e32 v6, 1, v4
	v_cmp_eq_u32_e32 vcc, 2, v6
	v_lshl_add_u32 v5, v6, 10, v5
	v_and_b32_e32 v4, 1, v4
	v_cndmask_b32_e32 v7, v11, v10, vcc
	v_lshl_add_u32 v5, v4, 7, v5
	v_add_u32_e32 v5, v7, v5
	global_load_dword v233, v5, s[12:13]
	v_add_u32_e32 v2, 128, v134
	v_mul_u32_u24_e32 v3, 0x2aab, v2
	v_lshrrev_b32_e32 v3, 16, v3
	v_mul_u32_u24_e32 v4, 6, v3
	v_sub_u32_e32 v4, v2, v4
	v_add_u32_e32 v5, s38, v3
	v_max_i32_e32 v5, 0, v5
	v_add_u32_e32 v5, s37, v5
	v_lshlrev_b32_e32 v5, 12, v5
	v_lshrrev_b32_e32 v6, 1, v4
	v_cmp_eq_u32_e32 vcc, 2, v6
	v_lshl_add_u32 v5, v6, 10, v5
	v_and_b32_e32 v4, 1, v4
	v_cndmask_b32_e32 v7, v11, v10, vcc
	v_lshl_add_u32 v5, v4, 7, v5
	v_add_u32_e32 v5, v7, v5
	global_load_dword v233, v5, s[12:13]
	v_add_u32_e32 v2, 192, v134
	v_mul_u32_u24_e32 v3, 0x2aab, v2
	v_lshrrev_b32_e32 v3, 16, v3
	v_mul_u32_u24_e32 v4, 6, v3
	v_sub_u32_e32 v4, v2, v4
	v_add_u32_e32 v5, s38, v3
	v_max_i32_e32 v5, 0, v5
	v_add_u32_e32 v5, s37, v5
	v_lshlrev_b32_e32 v5, 12, v5
	v_lshrrev_b32_e32 v6, 1, v4
	v_cmp_eq_u32_e32 vcc, 2, v6
	v_lshl_add_u32 v5, v6, 10, v5
	v_and_b32_e32 v4, 1, v4
	v_cndmask_b32_e32 v7, v11, v10, vcc
	v_lshl_add_u32 v5, v4, 7, v5
	v_add_u32_e32 v5, v7, v5
	global_load_dword v233, v5, s[12:13]
	v_add_u32_e32 v2, 256, v134
	v_mul_u32_u24_e32 v3, 0x2aab, v2
	v_lshrrev_b32_e32 v3, 16, v3
	v_mul_u32_u24_e32 v4, 6, v3
	v_sub_u32_e32 v4, v2, v4
	v_add_u32_e32 v5, s38, v3
	v_max_i32_e32 v5, 0, v5
	v_add_u32_e32 v5, s37, v5
	v_lshlrev_b32_e32 v5, 12, v5
	v_lshrrev_b32_e32 v6, 1, v4
	v_cmp_eq_u32_e32 vcc, 2, v6
	v_lshl_add_u32 v5, v6, 10, v5
	v_and_b32_e32 v4, 1, v4
	v_cndmask_b32_e32 v7, v11, v10, vcc
	v_lshl_add_u32 v5, v4, 7, v5
	v_add_u32_e32 v5, v7, v5
	global_load_dword v233, v5, s[12:13]
	v_add_u32_e32 v2, 320, v134
	v_mul_u32_u24_e32 v3, 0x2aab, v2
	v_lshrrev_b32_e32 v3, 16, v3
	v_mul_u32_u24_e32 v4, 6, v3
	v_sub_u32_e32 v4, v2, v4
	v_add_u32_e32 v5, s38, v3
	v_max_i32_e32 v5, 0, v5
	v_add_u32_e32 v5, s37, v5
	v_lshlrev_b32_e32 v5, 12, v5
	v_lshrrev_b32_e32 v6, 1, v4
	v_cmp_eq_u32_e32 vcc, 2, v6
	v_lshl_add_u32 v5, v6, 10, v5
	v_and_b32_e32 v4, 1, v4
	v_cndmask_b32_e32 v7, v11, v10, vcc
	v_lshl_add_u32 v5, v4, 7, v5
	v_add_u32_e32 v5, v7, v5
	global_load_dword v233, v5, s[12:13]
	v_add_u32_e32 v2, 384, v134
	v_mul_u32_u24_e32 v3, 0x2aab, v2
	v_lshrrev_b32_e32 v3, 16, v3
	v_mul_u32_u24_e32 v4, 6, v3
	v_sub_u32_e32 v4, v2, v4
	v_add_u32_e32 v5, s38, v3
	v_max_i32_e32 v5, 0, v5
	v_add_u32_e32 v5, s37, v5
	v_lshlrev_b32_e32 v5, 12, v5
	v_lshrrev_b32_e32 v6, 1, v4
	v_cmp_eq_u32_e32 vcc, 2, v6
	v_lshl_add_u32 v5, v6, 10, v5
	v_and_b32_e32 v4, 1, v4
	v_cndmask_b32_e32 v7, v11, v10, vcc
	v_lshl_add_u32 v5, v4, 7, v5
	v_add_u32_e32 v5, v7, v5
	global_load_dword v233, v5, s[12:13]
